# k15
# speedup vs baseline: 1.0055x; 1.0002x over previous
; __device__ __forceinline__ unsigned cvtpk(float lo, float hi) { f32x2 v = {lo, hi}; bf16x2_t b = __builtin_convertvector(v, bf16x2_t); return __builtin_bit_cast(unsigned, b); }
;     __device__ __forceinline__ void operator()(const f32x4 (&acc)[2][2][4][2], const Unit& u, int ui, int wr, int wc, int fr, int fq) const {
;     ...
;             for (int m = 0; m < 4; ++m) { const int rl = ai * HALF + wr * 64 + m * 16 + fr; const float rs = rsl[(ui & 1) * 256 + rl];
;                 float h[8];
; #pragma unroll
;                 for (int n = 0; n < 2; ++n)
; #pragma unroll
;                     for (int e = 0; e < 4; ++e) { const float g = acc[ai][0][m][n][e] * rs, up = acc[ai][1][m][n][e] * rs;
;                         h[n * 4 + e] = g * __builtin_amdgcn_rcpf(1.f + __builtin_amdgcn_exp2f(-g * LOG2E)) * up; }
;                 u32x4 w; w.x = cvtpk(h[0], h[1]); w.y = cvtpk(h[2], h[3]); w.z = cvtpk(h[4], h[5]); w.w = cvtpk(h[6], h[7]);
;                 *(u32x4*)(H + (size_t)(u.pm * 256 + rl) * DFF + col0) = w; }
.Lffnup_pf_skip:
	v_mbcnt_lo_u32_b32 v141, -1, 0
	v_mbcnt_hi_u32_b32 v141, -1, v141
	s_lshl_b32 s12, s38, 7
	v_ashrrev_i32_e32 v140, 1, v141
	s_or_b32 s12, s12, s69
	v_and_b32_e32 v140, -8, v140
	v_add_u32_e32 v140, s12, v140
	s_lshl_b32 s12, s37, 10
	s_and_b32 s12, s12, 0x400
	v_and_or_b32 v147, v141, 15, s68
	s_add_i32 s12, s12, 0
	v_lshl_add_u32 v142, v147, 2, s12
	v_add_u32_e32 v146, 0x20000, v142
	ds_read2_b32 v[142:143], v146 offset1:16
	ds_read2_b32 v[190:191], v146 offset0:32 offset1:48
	ds_read2_b32 v[192:193], v146 offset0:128 offset1:144
	ds_read2_b32 v[194:195], v146 offset0:160 offset1:176
	v_ashrrev_i32_e32 v141, 31, v140
	s_andn2_b64 vcc, exec, s[4:5]
	s_waitcnt lgkmcnt(0)
	v_mul_f32_e32 v170, 0xbfb8aa3b, v142
	v_mul_f32_e32 v172, v142, v142
	v_pk_mul_f32 v[182:183], v[126:127], v[122:123]
	v_pk_mul_f32 v[184:185], v[128:129], v[124:125]
	v_pk_mul_f32 v[186:187], v[118:119], v[114:115]
	v_pk_mul_f32 v[188:189], v[120:121], v[116:117]
	v_rcp_f32_e32 v172, v172
	v_pk_mul_f32 v[174:175], v[126:127], v[170:171] op_sel_hi:[1,0]
	v_pk_mul_f32 v[176:177], v[128:129], v[170:171] op_sel_hi:[1,0]
	v_pk_mul_f32 v[178:179], v[118:119], v[170:171] op_sel_hi:[1,0]
	v_pk_mul_f32 v[180:181], v[120:121], v[170:171] op_sel_hi:[1,0]
	v_exp_f32_e32 v174, v174
	v_exp_f32_e32 v175, v175
	v_exp_f32_e32 v176, v176
	v_exp_f32_e32 v177, v177
	v_exp_f32_e32 v178, v178
	v_exp_f32_e32 v179, v179
	v_exp_f32_e32 v180, v180
	v_exp_f32_e32 v181, v181
	v_pk_fma_f32 v[174:175], v[174:175], v[172:173], v[172:173] op_sel_hi:[1,0,0]
	v_pk_fma_f32 v[176:177], v[176:177], v[172:173], v[172:173] op_sel_hi:[1,0,0]
	v_pk_fma_f32 v[178:179], v[178:179], v[172:173], v[172:173] op_sel_hi:[1,0,0]
	v_pk_fma_f32 v[180:181], v[180:181], v[172:173], v[172:173] op_sel_hi:[1,0,0]
	v_rcp_f32_e32 v174, v174
	v_rcp_f32_e32 v175, v175
	v_rcp_f32_e32 v176, v176
	v_rcp_f32_e32 v177, v177
	v_rcp_f32_e32 v178, v178
	v_rcp_f32_e32 v179, v179
	v_rcp_f32_e32 v180, v180
	v_rcp_f32_e32 v181, v181
	v_pk_mul_f32 v[182:183], v[182:183], v[174:175]
	v_pk_mul_f32 v[184:185], v[184:185], v[176:177]
	v_pk_mul_f32 v[186:187], v[186:187], v[178:179]
	v_pk_mul_f32 v[188:189], v[188:189], v[180:181]
	v_lshl_add_u32 v118, s36, 8, v147
	v_mov_b64_e32 v[114:115], s[10:11]
	v_mad_i64_i32 v[124:125], s[34:35], v118, s55, v[114:115]
	v_lshlrev_b64 v[116:117], 1, v[140:141]
	v_lshl_add_u64 v[124:125], v[124:125], 0, v[116:117]
	v_cvt_pk_bf16_f32 v120, v182, v183
	v_cvt_pk_bf16_f32 v121, v184, v185
	v_cvt_pk_bf16_f32 v122, v186, v187
	v_cvt_pk_bf16_f32 v123, v188, v189
	global_store_dwordx4 v[124:125], v[120:123], off
	s_mov_b64 s[36:37], -1
	s_nop 0
	v_mul_f32_e32 v170, 0xbfb8aa3b, v143
	v_mul_f32_e32 v172, v143, v143
	v_pk_mul_f32 v[182:183], v[110:111], v[106:107]
	v_pk_mul_f32 v[184:185], v[112:113], v[108:109]
	v_pk_mul_f32 v[186:187], v[102:103], v[98:99]
	v_pk_mul_f32 v[188:189], v[104:105], v[100:101]
	v_rcp_f32_e32 v172, v172
	v_pk_mul_f32 v[174:175], v[110:111], v[170:171] op_sel_hi:[1,0]
	v_pk_mul_f32 v[176:177], v[112:113], v[170:171] op_sel_hi:[1,0]
	v_pk_mul_f32 v[178:179], v[102:103], v[170:171] op_sel_hi:[1,0]
	v_pk_mul_f32 v[180:181], v[104:105], v[170:171] op_sel_hi:[1,0]
	v_exp_f32_e32 v174, v174
	v_exp_f32_e32 v175, v175
	v_exp_f32_e32 v176, v176
	v_exp_f32_e32 v177, v177
	v_exp_f32_e32 v178, v178
	v_exp_f32_e32 v179, v179
	v_exp_f32_e32 v180, v180
	v_exp_f32_e32 v181, v181
	v_pk_fma_f32 v[174:175], v[174:175], v[172:173], v[172:173] op_sel_hi:[1,0,0]
	v_pk_fma_f32 v[176:177], v[176:177], v[172:173], v[172:173] op_sel_hi:[1,0,0]
	v_pk_fma_f32 v[178:179], v[178:179], v[172:173], v[172:173] op_sel_hi:[1,0,0]
	v_pk_fma_f32 v[180:181], v[180:181], v[172:173], v[172:173] op_sel_hi:[1,0,0]
	v_rcp_f32_e32 v174, v174
	v_rcp_f32_e32 v175, v175
	v_rcp_f32_e32 v176, v176
	v_rcp_f32_e32 v177, v177
	v_rcp_f32_e32 v178, v178
	v_rcp_f32_e32 v179, v179
	v_rcp_f32_e32 v180, v180
	v_rcp_f32_e32 v181, v181
	v_pk_mul_f32 v[182:183], v[182:183], v[174:175]
	v_pk_mul_f32 v[184:185], v[184:185], v[176:177]
	v_pk_mul_f32 v[186:187], v[186:187], v[178:179]
	v_pk_mul_f32 v[188:189], v[188:189], v[180:181]
	v_add_u32_e32 v102, 16, v118
	v_mad_i64_i32 v[102:103], s[34:35], v102, s55, v[114:115]
	v_lshl_add_u64 v[102:103], v[102:103], 0, v[116:117]
	v_cvt_pk_bf16_f32 v98, v182, v183
	v_cvt_pk_bf16_f32 v99, v184, v185
	v_cvt_pk_bf16_f32 v100, v186, v187
	v_cvt_pk_bf16_f32 v101, v188, v189
	global_store_dwordx4 v[102:103], v[98:101], off
	v_mul_f32_e32 v170, 0xbfb8aa3b, v190
	v_mul_f32_e32 v172, v190, v190
	v_pk_mul_f32 v[182:183], v[94:95], v[90:91]
	v_pk_mul_f32 v[184:185], v[96:97], v[92:93]
	v_pk_mul_f32 v[186:187], v[86:87], v[82:83]
	v_pk_mul_f32 v[188:189], v[88:89], v[84:85]
	v_rcp_f32_e32 v172, v172
	v_pk_mul_f32 v[174:175], v[94:95], v[170:171] op_sel_hi:[1,0]
	v_pk_mul_f32 v[176:177], v[96:97], v[170:171] op_sel_hi:[1,0]
	v_pk_mul_f32 v[178:179], v[86:87], v[170:171] op_sel_hi:[1,0]
	v_pk_mul_f32 v[180:181], v[88:89], v[170:171] op_sel_hi:[1,0]
	v_exp_f32_e32 v174, v174
	v_exp_f32_e32 v175, v175
	v_exp_f32_e32 v176, v176
	v_exp_f32_e32 v177, v177
	v_exp_f32_e32 v178, v178
	v_exp_f32_e32 v179, v179
	v_exp_f32_e32 v180, v180
	v_exp_f32_e32 v181, v181
	v_pk_fma_f32 v[174:175], v[174:175], v[172:173], v[172:173] op_sel_hi:[1,0,0]
	v_pk_fma_f32 v[176:177], v[176:177], v[172:173], v[172:173] op_sel_hi:[1,0,0]
	v_pk_fma_f32 v[178:179], v[178:179], v[172:173], v[172:173] op_sel_hi:[1,0,0]
	v_pk_fma_f32 v[180:181], v[180:181], v[172:173], v[172:173] op_sel_hi:[1,0,0]
	v_rcp_f32_e32 v174, v174
	v_rcp_f32_e32 v175, v175
	v_rcp_f32_e32 v176, v176
	v_rcp_f32_e32 v177, v177
	v_rcp_f32_e32 v178, v178
	v_rcp_f32_e32 v179, v179
; __device__ __forceinline__ unsigned cvtpk(float lo, float hi) { f32x2 v = {lo, hi}; bf16x2_t b = __builtin_convertvector(v, bf16x2_t); return __builtin_bit_cast(unsigned, b); }
;     __device__ __forceinline__ void operator()(const f32x4 (&acc)[2][2][4][2], const Unit& u, int ui, int wr, int wc, int fr, int fq) const {
;     ...
;             for (int m = 0; m < 4; ++m) { const int rl = ai * HALF + wr * 64 + m * 16 + fr; const float rs = rsl[(ui & 1) * 256 + rl];
;                 float h[8];
; #pragma unroll
;                 for (int n = 0; n < 2; ++n)
; #pragma unroll
;                     for (int e = 0; e < 4; ++e) { const float g = acc[ai][0][m][n][e] * rs, up = acc[ai][1][m][n][e] * rs;
;                         h[n * 4 + e] = g * __builtin_amdgcn_rcpf(1.f + __builtin_amdgcn_exp2f(-g * LOG2E)) * up; }
;                 u32x4 w; w.x = cvtpk(h[0], h[1]); w.y = cvtpk(h[2], h[3]); w.z = cvtpk(h[4], h[5]); w.w = cvtpk(h[6], h[7]);
;                 *(u32x4*)(H + (size_t)(u.pm * 256 + rl) * DFF + col0) = w; }
	v_rcp_f32_e32 v180, v180
	v_rcp_f32_e32 v181, v181
	v_pk_mul_f32 v[182:183], v[182:183], v[174:175]
	v_pk_mul_f32 v[184:185], v[184:185], v[176:177]
	v_pk_mul_f32 v[186:187], v[186:187], v[178:179]
	v_pk_mul_f32 v[188:189], v[188:189], v[180:181]
	v_add_u32_e32 v86, 32, v118
	v_mad_i64_i32 v[86:87], s[34:35], v86, s55, v[114:115]
	v_lshl_add_u64 v[86:87], v[86:87], 0, v[116:117]
	v_cvt_pk_bf16_f32 v82, v182, v183
	v_cvt_pk_bf16_f32 v83, v184, v185
	v_cvt_pk_bf16_f32 v84, v186, v187
	v_cvt_pk_bf16_f32 v85, v188, v189
	global_store_dwordx4 v[86:87], v[82:85], off
	s_nop 1
	v_mul_f32_e32 v170, 0xbfb8aa3b, v191
	v_mul_f32_e32 v172, v191, v191
	v_pk_mul_f32 v[182:183], v[78:79], v[74:75]
	v_pk_mul_f32 v[184:185], v[80:81], v[76:77]
	v_pk_mul_f32 v[186:187], v[70:71], v[66:67]
	v_pk_mul_f32 v[188:189], v[72:73], v[68:69]
	v_rcp_f32_e32 v172, v172
	v_pk_mul_f32 v[174:175], v[78:79], v[170:171] op_sel_hi:[1,0]
	v_pk_mul_f32 v[176:177], v[80:81], v[170:171] op_sel_hi:[1,0]
	v_pk_mul_f32 v[178:179], v[70:71], v[170:171] op_sel_hi:[1,0]
	v_pk_mul_f32 v[180:181], v[72:73], v[170:171] op_sel_hi:[1,0]
	v_exp_f32_e32 v174, v174
	v_exp_f32_e32 v175, v175
	v_exp_f32_e32 v176, v176
	v_exp_f32_e32 v177, v177
	v_exp_f32_e32 v178, v178
	v_exp_f32_e32 v179, v179
	v_exp_f32_e32 v180, v180
	v_exp_f32_e32 v181, v181
	v_pk_fma_f32 v[174:175], v[174:175], v[172:173], v[172:173] op_sel_hi:[1,0,0]
	v_pk_fma_f32 v[176:177], v[176:177], v[172:173], v[172:173] op_sel_hi:[1,0,0]
	v_pk_fma_f32 v[178:179], v[178:179], v[172:173], v[172:173] op_sel_hi:[1,0,0]
	v_pk_fma_f32 v[180:181], v[180:181], v[172:173], v[172:173] op_sel_hi:[1,0,0]
	v_rcp_f32_e32 v174, v174
	v_rcp_f32_e32 v175, v175
	v_rcp_f32_e32 v176, v176
	v_rcp_f32_e32 v177, v177
	v_rcp_f32_e32 v178, v178
	v_rcp_f32_e32 v179, v179
	v_rcp_f32_e32 v180, v180
	v_rcp_f32_e32 v181, v181
	v_pk_mul_f32 v[182:183], v[182:183], v[174:175]
	v_pk_mul_f32 v[184:185], v[184:185], v[176:177]
	v_pk_mul_f32 v[186:187], v[186:187], v[178:179]
	v_pk_mul_f32 v[188:189], v[188:189], v[180:181]
	v_add_u32_e32 v70, 48, v118
	v_mad_i64_i32 v[70:71], s[34:35], v70, s55, v[114:115]
	v_lshl_add_u64 v[70:71], v[70:71], 0, v[116:117]
	v_cvt_pk_bf16_f32 v66, v182, v183
	v_cvt_pk_bf16_f32 v67, v184, v185
	v_cvt_pk_bf16_f32 v68, v186, v187
	v_cvt_pk_bf16_f32 v69, v188, v189
	global_store_dwordx4 v[70:71], v[66:69], off
	v_mul_f32_e32 v170, 0xbfb8aa3b, v192
	v_mul_f32_e32 v172, v192, v192
	v_pk_mul_f32 v[182:183], v[62:63], v[58:59]
	v_pk_mul_f32 v[184:185], v[64:65], v[60:61]
	v_pk_mul_f32 v[186:187], v[54:55], v[50:51]
	v_pk_mul_f32 v[188:189], v[56:57], v[52:53]
	v_rcp_f32_e32 v172, v172
	v_pk_mul_f32 v[174:175], v[62:63], v[170:171] op_sel_hi:[1,0]
	v_pk_mul_f32 v[176:177], v[64:65], v[170:171] op_sel_hi:[1,0]
	v_pk_mul_f32 v[178:179], v[54:55], v[170:171] op_sel_hi:[1,0]
	v_pk_mul_f32 v[180:181], v[56:57], v[170:171] op_sel_hi:[1,0]
	v_exp_f32_e32 v174, v174
	v_exp_f32_e32 v175, v175
	v_exp_f32_e32 v176, v176
	v_exp_f32_e32 v177, v177
	v_exp_f32_e32 v178, v178
	v_exp_f32_e32 v179, v179
	v_exp_f32_e32 v180, v180
	v_exp_f32_e32 v181, v181
	v_pk_fma_f32 v[174:175], v[174:175], v[172:173], v[172:173] op_sel_hi:[1,0,0]
	v_pk_fma_f32 v[176:177], v[176:177], v[172:173], v[172:173] op_sel_hi:[1,0,0]
	v_pk_fma_f32 v[178:179], v[178:179], v[172:173], v[172:173] op_sel_hi:[1,0,0]
	v_pk_fma_f32 v[180:181], v[180:181], v[172:173], v[172:173] op_sel_hi:[1,0,0]
	v_rcp_f32_e32 v174, v174
	v_rcp_f32_e32 v175, v175
	v_rcp_f32_e32 v176, v176
	v_rcp_f32_e32 v177, v177
	v_rcp_f32_e32 v178, v178
	v_rcp_f32_e32 v179, v179
	v_rcp_f32_e32 v180, v180
	v_rcp_f32_e32 v181, v181
	v_pk_mul_f32 v[182:183], v[182:183], v[174:175]
	v_pk_mul_f32 v[184:185], v[184:185], v[176:177]
	v_pk_mul_f32 v[186:187], v[186:187], v[178:179]
	v_pk_mul_f32 v[188:189], v[188:189], v[180:181]
	v_add_u32_e32 v54, 0x80, v118
	v_mad_i64_i32 v[54:55], s[34:35], v54, s55, v[114:115]
	v_lshl_add_u64 v[54:55], v[54:55], 0, v[116:117]
	v_cvt_pk_bf16_f32 v50, v182, v183
	v_cvt_pk_bf16_f32 v51, v184, v185
	v_cvt_pk_bf16_f32 v52, v186, v187
	v_cvt_pk_bf16_f32 v53, v188, v189
	global_store_dwordx4 v[54:55], v[50:53], off
	s_nop 1
	v_mul_f32_e32 v170, 0xbfb8aa3b, v193
	v_mul_f32_e32 v172, v193, v193
	v_pk_mul_f32 v[182:183], v[46:47], v[42:43]
	v_pk_mul_f32 v[184:185], v[48:49], v[44:45]
	v_pk_mul_f32 v[186:187], v[38:39], v[34:35]
	v_pk_mul_f32 v[188:189], v[40:41], v[36:37]
	v_rcp_f32_e32 v172, v172
	v_pk_mul_f32 v[174:175], v[46:47], v[170:171] op_sel_hi:[1,0]
	v_pk_mul_f32 v[176:177], v[48:49], v[170:171] op_sel_hi:[1,0]
	v_pk_mul_f32 v[178:179], v[38:39], v[170:171] op_sel_hi:[1,0]
	v_pk_mul_f32 v[180:181], v[40:41], v[170:171] op_sel_hi:[1,0]
	v_exp_f32_e32 v174, v174
	v_exp_f32_e32 v175, v175
	v_exp_f32_e32 v176, v176
	v_exp_f32_e32 v177, v177
	v_exp_f32_e32 v178, v178
	v_exp_f32_e32 v179, v179
	v_exp_f32_e32 v180, v180
	v_exp_f32_e32 v181, v181
	v_pk_fma_f32 v[174:175], v[174:175], v[172:173], v[172:173] op_sel_hi:[1,0,0]
	v_pk_fma_f32 v[176:177], v[176:177], v[172:173], v[172:173] op_sel_hi:[1,0,0]
	v_pk_fma_f32 v[178:179], v[178:179], v[172:173], v[172:173] op_sel_hi:[1,0,0]
	v_pk_fma_f32 v[180:181], v[180:181], v[172:173], v[172:173] op_sel_hi:[1,0,0]
	v_rcp_f32_e32 v174, v174
	v_rcp_f32_e32 v175, v175
	v_rcp_f32_e32 v176, v176
	v_rcp_f32_e32 v177, v177
	v_rcp_f32_e32 v178, v178
	v_rcp_f32_e32 v179, v179
	v_rcp_f32_e32 v180, v180
	v_rcp_f32_e32 v181, v181
	v_pk_mul_f32 v[182:183], v[182:183], v[174:175]
	v_pk_mul_f32 v[184:185], v[184:185], v[176:177]
	v_pk_mul_f32 v[186:187], v[186:187], v[178:179]
; #define LAS __attribute__((address_space(3)))
; __device__ __forceinline__ unsigned cvtpk(float lo, float hi) { f32x2 v = {lo, hi}; bf16x2_t b = __builtin_convertvector(v, bf16x2_t); return __builtin_bit_cast(unsigned, b); }
; __device__ __forceinline__ int lane_id_asm() { int l; asm volatile("v_mbcnt_lo_u32_b32 %0, -1, 0\n\tv_mbcnt_hi_u32_b32 %0, -1, %0" : "=v"(l)); return l; }
; __device__ __forceinline__ void rs_prep(const float* ssq, int tok0, LAS float* rsl, int ui, int wv) {
;     const int tid = wv * 64 + lane_id_asm();
;     if (tid < 256) { const f32x4* s = (const f32x4*)(ssq + (size_t)(tok0 + tid) * 16); const f32x4 a = s[0], b = s[1], c = s[2], d = s[3];
;         const float t = ((a.x + a.y) + (a.z + a.w)) + ((b.x + b.y) + (b.z + b.w)) + ((c.x + c.y) + (c.z + c.w)) + ((d.x + d.y) + (d.z + d.w));
;         rsl[(ui & 1) * 256 + tid] = rsqrtf(t * (1.f / 1024.f) + EPS); }
;     __device__ __forceinline__ void operator()(const f32x4 (&acc)[2][2][4][2], const Unit& u, int ui, int wr, int wc, int fr, int fq) const {
;     ...
;             for (int m = 0; m < 4; ++m) { const int rl = ai * HALF + wr * 64 + m * 16 + fr; const float rs = rsl[(ui & 1) * 256 + rl];
;                 float h[8];
; #pragma unroll
;                 for (int n = 0; n < 2; ++n)
; #pragma unroll
;                     for (int e = 0; e < 4; ++e) { const float g = acc[ai][0][m][n][e] * rs, up = acc[ai][1][m][n][e] * rs;
;                         h[n * 4 + e] = g * __builtin_amdgcn_rcpf(1.f + __builtin_amdgcn_exp2f(-g * LOG2E)) * up; }
;                 u32x4 w; w.x = cvtpk(h[0], h[1]); w.y = cvtpk(h[2], h[3]); w.z = cvtpk(h[4], h[5]); w.w = cvtpk(h[6], h[7]);
;                 *(u32x4*)(H + (size_t)(u.pm * 256 + rl) * DFF + col0) = w; }
	v_pk_mul_f32 v[188:189], v[188:189], v[180:181]
	v_add_u32_e32 v38, 0x90, v118
	v_mad_i64_i32 v[38:39], s[34:35], v38, s55, v[114:115]
	v_lshl_add_u64 v[38:39], v[38:39], 0, v[116:117]
	v_cvt_pk_bf16_f32 v34, v182, v183
	v_cvt_pk_bf16_f32 v35, v184, v185
	v_cvt_pk_bf16_f32 v36, v186, v187
	v_cvt_pk_bf16_f32 v37, v188, v189
	global_store_dwordx4 v[38:39], v[34:37], off
	v_mul_f32_e32 v170, 0xbfb8aa3b, v194
	v_mul_f32_e32 v172, v194, v194
	v_pk_mul_f32 v[182:183], v[30:31], v[26:27]
	v_pk_mul_f32 v[184:185], v[32:33], v[28:29]
	v_pk_mul_f32 v[186:187], v[22:23], v[18:19]
	v_pk_mul_f32 v[188:189], v[24:25], v[20:21]
	v_rcp_f32_e32 v172, v172
	v_pk_mul_f32 v[174:175], v[30:31], v[170:171] op_sel_hi:[1,0]
	v_pk_mul_f32 v[176:177], v[32:33], v[170:171] op_sel_hi:[1,0]
	v_pk_mul_f32 v[178:179], v[22:23], v[170:171] op_sel_hi:[1,0]
	v_pk_mul_f32 v[180:181], v[24:25], v[170:171] op_sel_hi:[1,0]
	v_exp_f32_e32 v174, v174
	v_exp_f32_e32 v175, v175
	v_exp_f32_e32 v176, v176
	v_exp_f32_e32 v177, v177
	v_exp_f32_e32 v178, v178
	v_exp_f32_e32 v179, v179
	v_exp_f32_e32 v180, v180
	v_exp_f32_e32 v181, v181
	v_pk_fma_f32 v[174:175], v[174:175], v[172:173], v[172:173] op_sel_hi:[1,0,0]
	v_pk_fma_f32 v[176:177], v[176:177], v[172:173], v[172:173] op_sel_hi:[1,0,0]
	v_pk_fma_f32 v[178:179], v[178:179], v[172:173], v[172:173] op_sel_hi:[1,0,0]
	v_pk_fma_f32 v[180:181], v[180:181], v[172:173], v[172:173] op_sel_hi:[1,0,0]
	v_rcp_f32_e32 v174, v174
	v_rcp_f32_e32 v175, v175
	v_rcp_f32_e32 v176, v176
	v_rcp_f32_e32 v177, v177
	v_rcp_f32_e32 v178, v178
	v_rcp_f32_e32 v179, v179
	v_rcp_f32_e32 v180, v180
	v_rcp_f32_e32 v181, v181
	v_pk_mul_f32 v[182:183], v[182:183], v[174:175]
	v_pk_mul_f32 v[184:185], v[184:185], v[176:177]
	v_pk_mul_f32 v[186:187], v[186:187], v[178:179]
	v_pk_mul_f32 v[188:189], v[188:189], v[180:181]
	v_add_u32_e32 v22, 0xa0, v118
	v_mad_i64_i32 v[22:23], s[34:35], v22, s55, v[114:115]
	v_lshl_add_u64 v[22:23], v[22:23], 0, v[116:117]
	v_cvt_pk_bf16_f32 v18, v182, v183
	v_cvt_pk_bf16_f32 v19, v184, v185
	v_cvt_pk_bf16_f32 v20, v186, v187
	v_cvt_pk_bf16_f32 v21, v188, v189
	global_store_dwordx4 v[22:23], v[18:21], off
	s_nop 1
	v_mul_f32_e32 v170, 0xbfb8aa3b, v195
	v_mul_f32_e32 v172, v195, v195
	v_pk_mul_f32 v[182:183], v[14:15], v[10:11]
	v_pk_mul_f32 v[184:185], v[16:17], v[12:13]
	v_pk_mul_f32 v[186:187], v[6:7], v[2:3]
	v_pk_mul_f32 v[188:189], v[8:9], v[4:5]
	v_rcp_f32_e32 v172, v172
	v_pk_mul_f32 v[174:175], v[14:15], v[170:171] op_sel_hi:[1,0]
	v_pk_mul_f32 v[176:177], v[16:17], v[170:171] op_sel_hi:[1,0]
	v_pk_mul_f32 v[178:179], v[6:7], v[170:171] op_sel_hi:[1,0]
	v_pk_mul_f32 v[180:181], v[8:9], v[170:171] op_sel_hi:[1,0]
	v_exp_f32_e32 v174, v174
	v_exp_f32_e32 v175, v175
	v_exp_f32_e32 v176, v176
	v_exp_f32_e32 v177, v177
	v_exp_f32_e32 v178, v178
	v_exp_f32_e32 v179, v179
	v_exp_f32_e32 v180, v180
	v_exp_f32_e32 v181, v181
	v_pk_fma_f32 v[174:175], v[174:175], v[172:173], v[172:173] op_sel_hi:[1,0,0]
	v_pk_fma_f32 v[176:177], v[176:177], v[172:173], v[172:173] op_sel_hi:[1,0,0]
	v_pk_fma_f32 v[178:179], v[178:179], v[172:173], v[172:173] op_sel_hi:[1,0,0]
	v_pk_fma_f32 v[180:181], v[180:181], v[172:173], v[172:173] op_sel_hi:[1,0,0]
	v_rcp_f32_e32 v174, v174
	v_rcp_f32_e32 v175, v175
	v_rcp_f32_e32 v176, v176
	v_rcp_f32_e32 v177, v177
	v_rcp_f32_e32 v178, v178
	v_rcp_f32_e32 v179, v179
	v_rcp_f32_e32 v180, v180
	v_rcp_f32_e32 v181, v181
	v_pk_mul_f32 v[182:183], v[182:183], v[174:175]
	v_pk_mul_f32 v[184:185], v[184:185], v[176:177]
	v_pk_mul_f32 v[186:187], v[186:187], v[178:179]
	v_pk_mul_f32 v[188:189], v[188:189], v[180:181]
	v_add_u32_e32 v6, 0xb0, v118
	v_mad_i64_i32 v[6:7], s[34:35], v6, s55, v[114:115]
	v_lshl_add_u64 v[6:7], v[6:7], 0, v[116:117]
	v_cvt_pk_bf16_f32 v2, v182, v183
	v_cvt_pk_bf16_f32 v3, v184, v185
	v_cvt_pk_bf16_f32 v4, v186, v187
	v_cvt_pk_bf16_f32 v5, v188, v189
	global_store_dwordx4 v[6:7], v[2:5], off
	s_cbranch_vccnz .LBB0_1159
	s_nop 0
	v_mbcnt_lo_u32_b32 v2, -1, 0
	v_mbcnt_hi_u32_b32 v2, -1, v2
	s_nop 0
	v_add_u32_e32 v2, s16, v2
	v_cmp_gt_i32_e32 vcc, s88, v2
	s_and_saveexec_b64 s[4:5], vcc
	s_cbranch_execz .LBB0_1169
	s_lshl_b32 s12, s82, 10
	s_and_b32 s12, s12, 0x400
	s_add_i32 s12, s12, 0
	v_lshl_add_u32 v2, v2, 2, s12
	v_add_u32_e32 v2, 0x20000, v2
	s_waitcnt vmcnt(8)
	v_mov_b64_e32 v[4:5], v[154:155]
	v_mov_b64_e32 v[6:7], v[156:157]
	v_mov_b64_e32 v[8:9], v[158:159]
	v_mov_b64_e32 v[10:11], v[160:161]
	v_mov_b64_e32 v[12:13], v[162:163]
	v_mov_b64_e32 v[14:15], v[164:165]
	v_mov_b64_e32 v[16:17], v[166:167]
	v_mov_b64_e32 v[18:19], v[168:169]
	v_add_f32_e32 v8, v8, v9
	v_add_f32_e32 v10, v10, v11
	v_mov_b32_e32 v20, v17
	v_mov_b32_e32 v21, v18
	v_mov_b32_e32 v17, v19
	v_mov_b32_e32 v18, v13
	v_mov_b32_e32 v19, v14
	v_mov_b32_e32 v13, v15
	v_pk_add_f32 v[16:17], v[20:21], v[16:17]
	v_pk_add_f32 v[12:13], v[18:19], v[12:13]
	v_pk_add_f32 v[16:17], v[16:17], v[16:17] op_sel:[0,1] op_sel_hi:[1,0]
	v_pk_add_f32 v[12:13], v[12:13], v[12:13] op_sel:[0,1] op_sel_hi:[1,0]
	v_mov_b32_e32 v17, v4
	v_mov_b32_e32 v13, v5
	v_mov_b32_e32 v9, v6
	v_mov_b32_e32 v11, v7
	v_pk_add_f32 v[4:5], v[16:17], v[12:13]
	v_pk_add_f32 v[6:7], v[8:9], v[10:11]
	s_nop 0
	v_pk_add_f32 v[4:5], v[4:5], v[6:7]
	s_nop 0
	v_add_f32_e32 v3, v4, v5
	v_fmamk_f32 v3, v3, 0x3a800000, v254
	v_cmp_gt_f32_e32 vcc, s56, v3
	v_mul_f32_e32 v4, 0x4b800000, v3
	s_nop 0
	v_cndmask_b32_e32 v3, v3, v4, vcc
	v_rsq_f32_e32 v3, v3
	s_nop 0
	v_mul_f32_e32 v4, 0x45800000, v3
	v_cndmask_b32_e32 v3, v3, v4, vcc
	ds_write_b32 v2, v3
